# MFMA-VALU interleave: sample-attention QK epilogue of one tile pair runs under the next pair's MFMAs
# baseline (speedup 1.0000x reference)
; #define LAS __attribute__((address_space(3)))
; __device__ __forceinline__ void attn_sample_unit(LAS unsigned char* lds, CArgsP a, int b, int h) {
;     ...
;     for (int j = tid; j < SA_NK; j += 512) {
;         const float* kp = j < PAST ? ck + (((size_t)b * PAST + j) * 8 + h) * 64 : nk + (size_t)(16 * b + (j - PAST)) * 512 + h * 64;
;         float acc[16];
; #pragma unroll
;         for (int t = 0; t < 16; ++t) acc[t] = 0.f;
; #pragma unroll
;         for (int hb = 0; hb < 2; ++hb) {
;             f32x4 kr[8];
; #pragma unroll
;             for (int i = 0; i < 8; ++i) kr[i] = *(const f32x4*)(kp + 32 * hb + 4 * i);
; #pragma unroll
;             for (int i = 0; i < 8; ++i) {
;                 asm volatile("" ::: "memory");
;                 const f32x4 k4 = kr[i];
; #pragma unroll
;                 for (int t = 0; t < 16; ++t) { const f32x4 q4 = *(const LAS f32x4*)(Qs + t * 64 + 32 * hb + 4 * i); acc[t] += (q4[0] * k4[0] + q4[1] * k4[1]) + (q4[2] * k4[2] + q4[3] * k4[3]); }
;             }
;         }
.Lqk_noext1:
	ds_read_b32 v140, v138 offset:0
	ds_read_b32 v141, v138 offset:512
	s_waitcnt lgkmcnt(2)
	v_mfma_f32_16x16x4_f32 v[16:19], v0, v28, 0
	v_mfma_f32_16x16x4_f32 v[20:23], v0, v52, 0
	v_mfma_f32_16x16x4_f32 v[16:19], v1, v29, v[16:19]
	v_mfma_f32_16x16x4_f32 v[20:23], v1, v53, v[20:23]
	v_mfma_f32_16x16x4_f32 v[16:19], v2, v30, v[16:19]
	v_mfma_f32_16x16x4_f32 v[20:23], v2, v54, v[20:23]
	v_mfma_f32_16x16x4_f32 v[16:19], v3, v31, v[16:19]
	v_mfma_f32_16x16x4_f32 v[20:23], v3, v55, v[20:23]
	v_mfma_f32_16x16x4_f32 v[16:19], v4, v32, v[16:19]
	v_mfma_f32_16x16x4_f32 v[20:23], v4, v56, v[20:23]
	v_mfma_f32_16x16x4_f32 v[16:19], v5, v33, v[16:19]
	v_mfma_f32_16x16x4_f32 v[20:23], v5, v57, v[20:23]
	v_mfma_f32_16x16x4_f32 v[16:19], v6, v34, v[16:19]
	v_mfma_f32_16x16x4_f32 v[20:23], v6, v58, v[20:23]
	v_mfma_f32_16x16x4_f32 v[16:19], v7, v35, v[16:19]
	v_mfma_f32_16x16x4_f32 v[20:23], v7, v59, v[20:23]
	v_mfma_f32_16x16x4_f32 v[16:19], v8, v36, v[16:19]
	v_mfma_f32_16x16x4_f32 v[20:23], v8, v60, v[20:23]
	v_mfma_f32_16x16x4_f32 v[16:19], v9, v37, v[16:19]
	v_mfma_f32_16x16x4_f32 v[20:23], v9, v61, v[20:23]
	v_mfma_f32_16x16x4_f32 v[16:19], v10, v38, v[16:19]
	v_mfma_f32_16x16x4_f32 v[20:23], v10, v62, v[20:23]
	v_mfma_f32_16x16x4_f32 v[16:19], v11, v39, v[16:19]
	v_mfma_f32_16x16x4_f32 v[20:23], v11, v63, v[20:23]
	v_mfma_f32_16x16x4_f32 v[16:19], v12, v40, v[16:19]
	v_mfma_f32_16x16x4_f32 v[20:23], v12, v64, v[20:23]
	v_mfma_f32_16x16x4_f32 v[16:19], v13, v41, v[16:19]
	v_mfma_f32_16x16x4_f32 v[20:23], v13, v65, v[20:23]
	v_mfma_f32_16x16x4_f32 v[16:19], v14, v42, v[16:19]
	v_mfma_f32_16x16x4_f32 v[20:23], v14, v66, v[20:23]
	v_mfma_f32_16x16x4_f32 v[16:19], v15, v43, v[16:19]
	v_mfma_f32_16x16x4_f32 v[20:23], v15, v67, v[20:23]
	s_add_u32 s48, s42, 0x0
	s_addc_u32 s49, s43, 0
	global_load_dwordx4 v[28:31], v136, s[48:49] offset:0
	global_load_dwordx4 v[32:35], v136, s[48:49] offset:2048
	global_load_dwordx4 v[36:39], v137, s[48:49] offset:0
	global_load_dwordx4 v[40:43], v137, s[48:49] offset:2048
	s_add_u32 s48, s42, 0x40000
	s_addc_u32 s49, s43, 0
	global_load_dwordx4 v[52:55], v136, s[48:49] offset:0
	global_load_dwordx4 v[56:59], v136, s[48:49] offset:2048
	global_load_dwordx4 v[60:63], v137, s[48:49] offset:0
	global_load_dwordx4 v[64:67], v137, s[48:49] offset:2048
	ds_read_b32 v142, v138 offset:1024
	ds_read_b32 v143, v138 offset:1536
	v_mfma_f32_16x16x4_f32 v[160:163], v0, v68, 0
	v_mfma_f32_16x16x4_f32 v[166:169], v0, v84, 0
	v_mfma_f32_16x16x4_f32 v[160:163], v1, v69, v[160:163]
	v_mfma_f32_16x16x4_f32 v[166:169], v1, v85, v[166:169]
	v_mfma_f32_16x16x4_f32 v[160:163], v2, v70, v[160:163]
	v_mfma_f32_16x16x4_f32 v[166:169], v2, v86, v[166:169]
	v_mfma_f32_16x16x4_f32 v[160:163], v3, v71, v[160:163]
	v_mfma_f32_16x16x4_f32 v[166:169], v3, v87, v[166:169]
	v_mfma_f32_16x16x4_f32 v[160:163], v4, v72, v[160:163]
	v_mfma_f32_16x16x4_f32 v[166:169], v4, v88, v[166:169]
	v_mfma_f32_16x16x4_f32 v[160:163], v5, v73, v[160:163]
	v_mfma_f32_16x16x4_f32 v[166:169], v5, v89, v[166:169]
	v_mfma_f32_16x16x4_f32 v[160:163], v6, v74, v[160:163]
	v_mfma_f32_16x16x4_f32 v[166:169], v6, v90, v[166:169]
	v_mfma_f32_16x16x4_f32 v[160:163], v7, v75, v[160:163]
	v_mfma_f32_16x16x4_f32 v[166:169], v7, v91, v[166:169]
	v_mfma_f32_16x16x4_f32 v[160:163], v8, v76, v[160:163]
	v_mfma_f32_16x16x4_f32 v[166:169], v8, v92, v[166:169]
	v_mfma_f32_16x16x4_f32 v[160:163], v9, v77, v[160:163]
	v_mfma_f32_16x16x4_f32 v[166:169], v9, v93, v[166:169]
	v_mfma_f32_16x16x4_f32 v[160:163], v10, v78, v[160:163]
	v_mfma_f32_16x16x4_f32 v[166:169], v10, v94, v[166:169]
	v_mfma_f32_16x16x4_f32 v[160:163], v11, v79, v[160:163]
	v_mfma_f32_16x16x4_f32 v[166:169], v11, v95, v[166:169]
	v_mfma_f32_16x16x4_f32 v[160:163], v12, v80, v[160:163]
	v_mfma_f32_16x16x4_f32 v[166:169], v12, v96, v[166:169]
	v_mfma_f32_16x16x4_f32 v[160:163], v13, v81, v[160:163]
	v_mfma_f32_16x16x4_f32 v[166:169], v13, v97, v[166:169]
	v_mfma_f32_16x16x4_f32 v[160:163], v14, v82, v[160:163]
	v_mfma_f32_16x16x4_f32 v[166:169], v14, v98, v[166:169]
	v_mfma_f32_16x16x4_f32 v[160:163], v15, v83, v[160:163]
	v_mfma_f32_16x16x4_f32 v[166:169], v15, v99, v[166:169]
	s_add_u32 s48, s42, 0x80000
	s_addc_u32 s49, s43, 0
	global_load_dwordx4 v[68:71], v136, s[48:49] offset:0
	global_load_dwordx4 v[72:75], v136, s[48:49] offset:2048
	global_load_dwordx4 v[76:79], v137, s[48:49] offset:0
	global_load_dwordx4 v[80:83], v137, s[48:49] offset:2048
	s_add_u32 s48, s42, 0xc0000
	s_addc_u32 s49, s43, 0
	global_load_dwordx4 v[84:87], v136, s[48:49] offset:0
	global_load_dwordx4 v[88:91], v136, s[48:49] offset:2048
	global_load_dwordx4 v[92:95], v137, s[48:49] offset:0
	global_load_dwordx4 v[96:99], v137, s[48:49] offset:2048
	s_waitcnt lgkmcnt(0)
; #define LAS __attribute__((address_space(3)))
; __device__ __forceinline__ void attn_sample_unit(LAS unsigned char* lds, CArgsP a, int b, int h) {
;     ...
;     for (int j = tid; j < SA_NK; j += 512) {
;         const float* kp = j < PAST ? ck + (((size_t)b * PAST + j) * 8 + h) * 64 : nk + (size_t)(16 * b + (j - PAST)) * 512 + h * 64;
;         float acc[16];
; #pragma unroll
;         for (int t = 0; t < 16; ++t) acc[t] = 0.f;
; #pragma unroll
;         for (int hb = 0; hb < 2; ++hb) {
;             f32x4 kr[8];
; #pragma unroll
;             for (int i = 0; i < 8; ++i) kr[i] = *(const f32x4*)(kp + 32 * hb + 4 * i);
; #pragma unroll
;             for (int i = 0; i < 8; ++i) {
;                 asm volatile("" ::: "memory");
;                 const f32x4 k4 = kr[i];
; #pragma unroll
;                 for (int t = 0; t < 16; ++t) { const f32x4 q4 = *(const LAS f32x4*)(Qs + t * 64 + 32 * hb + 4 * i); acc[t] += (q4[0] * k4[0] + q4[1] * k4[1]) + (q4[2] * k4[2] + q4[3] * k4[3]); }
;             }
;         }
;         const float cj = C[j];
; #pragma unroll
;         for (int t = 0; t < 16; ++t) SC[t * SA_NK + j] = acc[t] + (C[PAST + t] - cj) * LOG2E;
	v_sub_f32_e32 v44, v24, v140
	v_sub_f32_e32 v45, v25, v140
	v_sub_f32_e32 v46, v26, v140
	v_sub_f32_e32 v47, v27, v140
	v_fma_f32 v44, v44, s47, v16
	v_fma_f32 v45, v45, s47, v17
	v_fma_f32 v46, v46, s47, v18
	v_fma_f32 v47, v47, s47, v19
	ds_write_b32 v139, v44 offset:0
	ds_write_b32 v139, v45 offset:4160
	ds_write_b32 v139, v46 offset:8320
	ds_write_b32 v139, v47 offset:12480
	v_sub_f32_e32 v44, v24, v141
	v_sub_f32_e32 v45, v25, v141
	v_sub_f32_e32 v46, v26, v141
	v_sub_f32_e32 v47, v27, v141
	v_fma_f32 v44, v44, s47, v20
	v_fma_f32 v45, v45, s47, v21
	v_fma_f32 v46, v46, s47, v22
	v_fma_f32 v47, v47, s47, v23
	ds_write_b32 v139, v44 offset:512
	ds_write_b32 v139, v45 offset:4672
	ds_write_b32 v139, v46 offset:8832
	ds_write_b32 v139, v47 offset:12992
	ds_read_b32 v140, v138 offset:2048
	ds_read_b32 v141, v138 offset:2560
	v_mfma_f32_16x16x4_f32 v[16:19], v0, v104, 0
	v_mfma_f32_16x16x4_f32 v[20:23], v0, v120, 0
	v_mfma_f32_16x16x4_f32 v[16:19], v1, v105, v[16:19]
	v_mfma_f32_16x16x4_f32 v[20:23], v1, v121, v[20:23]
	v_mfma_f32_16x16x4_f32 v[16:19], v2, v106, v[16:19]
	v_mfma_f32_16x16x4_f32 v[20:23], v2, v122, v[20:23]
	v_mfma_f32_16x16x4_f32 v[16:19], v3, v107, v[16:19]
	v_mfma_f32_16x16x4_f32 v[20:23], v3, v123, v[20:23]
	v_mfma_f32_16x16x4_f32 v[16:19], v4, v108, v[16:19]
	v_mfma_f32_16x16x4_f32 v[20:23], v4, v124, v[20:23]
	v_mfma_f32_16x16x4_f32 v[16:19], v5, v109, v[16:19]
	v_mfma_f32_16x16x4_f32 v[20:23], v5, v125, v[20:23]
	v_mfma_f32_16x16x4_f32 v[16:19], v6, v110, v[16:19]
	v_mfma_f32_16x16x4_f32 v[20:23], v6, v126, v[20:23]
	v_mfma_f32_16x16x4_f32 v[16:19], v7, v111, v[16:19]
	v_mfma_f32_16x16x4_f32 v[20:23], v7, v127, v[20:23]
	v_mfma_f32_16x16x4_f32 v[16:19], v8, v112, v[16:19]
	v_mfma_f32_16x16x4_f32 v[20:23], v8, v128, v[20:23]
	v_mfma_f32_16x16x4_f32 v[16:19], v9, v113, v[16:19]
	v_mfma_f32_16x16x4_f32 v[20:23], v9, v129, v[20:23]
	v_mfma_f32_16x16x4_f32 v[16:19], v10, v114, v[16:19]
	v_mfma_f32_16x16x4_f32 v[20:23], v10, v130, v[20:23]
	v_mfma_f32_16x16x4_f32 v[16:19], v11, v115, v[16:19]
	v_mfma_f32_16x16x4_f32 v[20:23], v11, v131, v[20:23]
	v_mfma_f32_16x16x4_f32 v[16:19], v12, v116, v[16:19]
	v_mfma_f32_16x16x4_f32 v[20:23], v12, v132, v[20:23]
	v_mfma_f32_16x16x4_f32 v[16:19], v13, v117, v[16:19]
	v_mfma_f32_16x16x4_f32 v[20:23], v13, v133, v[20:23]
	v_mfma_f32_16x16x4_f32 v[16:19], v14, v118, v[16:19]
	v_mfma_f32_16x16x4_f32 v[20:23], v14, v134, v[20:23]
	v_mfma_f32_16x16x4_f32 v[16:19], v15, v119, v[16:19]
	v_mfma_f32_16x16x4_f32 v[20:23], v15, v135, v[20:23]
	s_add_u32 s48, s42, 0x100000
	s_addc_u32 s49, s43, 0
	global_load_dwordx4 v[104:107], v136, s[48:49] offset:0
	global_load_dwordx4 v[108:111], v136, s[48:49] offset:2048
	global_load_dwordx4 v[112:115], v137, s[48:49] offset:0
	global_load_dwordx4 v[116:119], v137, s[48:49] offset:2048
	s_add_u32 s48, s42, 0x140000
	s_addc_u32 s49, s43, 0
	global_load_dwordx4 v[120:123], v136, s[48:49] offset:0
	global_load_dwordx4 v[124:127], v136, s[48:49] offset:2048
	global_load_dwordx4 v[128:131], v137, s[48:49] offset:0
	global_load_dwordx4 v[132:135], v137, s[48:49] offset:2048
	s_waitcnt lgkmcnt(0)
; #define LAS __attribute__((address_space(3)))
; __device__ __forceinline__ void attn_sample_unit(LAS unsigned char* lds, CArgsP a, int b, int h) {
;     ...
;     for (int j = tid; j < SA_NK; j += 512) {
;         const float* kp = j < PAST ? ck + (((size_t)b * PAST + j) * 8 + h) * 64 : nk + (size_t)(16 * b + (j - PAST)) * 512 + h * 64;
;         float acc[16];
; #pragma unroll
;         for (int t = 0; t < 16; ++t) acc[t] = 0.f;
; #pragma unroll
;         for (int hb = 0; hb < 2; ++hb) {
;             f32x4 kr[8];
; #pragma unroll
;             for (int i = 0; i < 8; ++i) kr[i] = *(const f32x4*)(kp + 32 * hb + 4 * i);
; #pragma unroll
;             for (int i = 0; i < 8; ++i) {
;                 asm volatile("" ::: "memory");
;                 const f32x4 k4 = kr[i];
; #pragma unroll
;                 for (int t = 0; t < 16; ++t) { const f32x4 q4 = *(const LAS f32x4*)(Qs + t * 64 + 32 * hb + 4 * i); acc[t] += (q4[0] * k4[0] + q4[1] * k4[1]) + (q4[2] * k4[2] + q4[3] * k4[3]); }
;             }
;         }
;         const float cj = C[j];
; #pragma unroll
;         for (int t = 0; t < 16; ++t) SC[t * SA_NK + j] = acc[t] + (C[PAST + t] - cj) * LOG2E;
;     }
;     __syncthreads();
; #pragma unroll
;     for (int tt = 0; tt < 2; ++tt) {
;         const int t = 2 * wid + tt; LAS float* row = SC + t * SA_NK;
;         float mx = -INFINITY;
;         for (int j = lane; j < SA_NK; j += 64) { if (j > PAST + t) row[j] = -INFINITY; mx = fmaxf(mx, row[j]); }
	v_sub_f32_e32 v44, v24, v142
	v_sub_f32_e32 v45, v25, v142
	v_sub_f32_e32 v46, v26, v142
	v_sub_f32_e32 v47, v27, v142
	v_fma_f32 v44, v44, s47, v160
	v_fma_f32 v45, v45, s47, v161
	v_fma_f32 v46, v46, s47, v162
	v_fma_f32 v47, v47, s47, v163
	ds_write_b32 v139, v44 offset:1024
	ds_write_b32 v139, v45 offset:5184
	ds_write_b32 v139, v46 offset:9344
	ds_write_b32 v139, v47 offset:13504
	v_sub_f32_e32 v44, v24, v143
	v_sub_f32_e32 v45, v25, v143
	v_sub_f32_e32 v46, v26, v143
	v_sub_f32_e32 v47, v27, v143
	v_fma_f32 v44, v44, s47, v166
	v_fma_f32 v45, v45, s47, v167
	v_fma_f32 v46, v46, s47, v168
	v_fma_f32 v47, v47, s47, v169
	ds_write_b32 v139, v44 offset:1536
	ds_write_b32 v139, v45 offset:5696
	ds_write_b32 v139, v46 offset:9856
	ds_write_b32 v139, v47 offset:14016
	ds_read_b32 v142, v138 offset:3072
	ds_read_b32 v143, v138 offset:3584
	v_mfma_f32_16x16x4_f32 v[160:163], v0, v202, 0
	v_mfma_f32_16x16x4_f32 v[166:169], v0, v218, 0
	v_mfma_f32_16x16x4_f32 v[160:163], v1, v203, v[160:163]
	v_mfma_f32_16x16x4_f32 v[166:169], v1, v219, v[166:169]
	v_mfma_f32_16x16x4_f32 v[160:163], v2, v204, v[160:163]
	v_mfma_f32_16x16x4_f32 v[166:169], v2, v220, v[166:169]
	v_mfma_f32_16x16x4_f32 v[160:163], v3, v205, v[160:163]
	v_mfma_f32_16x16x4_f32 v[166:169], v3, v221, v[166:169]
	v_mfma_f32_16x16x4_f32 v[160:163], v4, v206, v[160:163]
	v_mfma_f32_16x16x4_f32 v[166:169], v4, v222, v[166:169]
	v_mfma_f32_16x16x4_f32 v[160:163], v5, v207, v[160:163]
	v_mfma_f32_16x16x4_f32 v[166:169], v5, v223, v[166:169]
	v_mfma_f32_16x16x4_f32 v[160:163], v6, v208, v[160:163]
	v_mfma_f32_16x16x4_f32 v[166:169], v6, v224, v[166:169]
	v_mfma_f32_16x16x4_f32 v[160:163], v7, v209, v[160:163]
	v_mfma_f32_16x16x4_f32 v[166:169], v7, v225, v[166:169]
	v_mfma_f32_16x16x4_f32 v[160:163], v8, v210, v[160:163]
	v_mfma_f32_16x16x4_f32 v[166:169], v8, v226, v[166:169]
	v_mfma_f32_16x16x4_f32 v[160:163], v9, v211, v[160:163]
	v_mfma_f32_16x16x4_f32 v[166:169], v9, v227, v[166:169]
	v_mfma_f32_16x16x4_f32 v[160:163], v10, v212, v[160:163]
	v_mfma_f32_16x16x4_f32 v[166:169], v10, v228, v[166:169]
	v_mfma_f32_16x16x4_f32 v[160:163], v11, v213, v[160:163]
	v_mfma_f32_16x16x4_f32 v[166:169], v11, v229, v[166:169]
	v_mfma_f32_16x16x4_f32 v[160:163], v12, v214, v[160:163]
	v_mfma_f32_16x16x4_f32 v[166:169], v12, v230, v[166:169]
	v_mfma_f32_16x16x4_f32 v[160:163], v13, v215, v[160:163]
	v_mfma_f32_16x16x4_f32 v[166:169], v13, v231, v[166:169]
	v_mfma_f32_16x16x4_f32 v[160:163], v14, v216, v[160:163]
	v_mfma_f32_16x16x4_f32 v[166:169], v14, v232, v[166:169]
	v_mfma_f32_16x16x4_f32 v[160:163], v15, v217, v[160:163]
	v_mfma_f32_16x16x4_f32 v[166:169], v15, v233, v[166:169]
	s_add_u32 s48, s42, 0x180000
	s_addc_u32 s49, s43, 0
	global_load_dwordx4 v[202:205], v136, s[48:49] offset:0
	global_load_dwordx4 v[206:209], v136, s[48:49] offset:2048
	global_load_dwordx4 v[210:213], v137, s[48:49] offset:0
	global_load_dwordx4 v[214:217], v137, s[48:49] offset:2048
	s_add_u32 s48, s42, 0x1c0000
	s_addc_u32 s49, s43, 0
	global_load_dwordx4 v[218:221], v136, s[48:49] offset:0
	global_load_dwordx4 v[222:225], v136, s[48:49] offset:2048
	global_load_dwordx4 v[226:229], v137, s[48:49] offset:0
	global_load_dwordx4 v[230:233], v137, s[48:49] offset:2048
	s_waitcnt lgkmcnt(0)
	v_sub_f32_e32 v44, v24, v140
	v_sub_f32_e32 v45, v25, v140
	v_sub_f32_e32 v46, v26, v140
	v_sub_f32_e32 v47, v27, v140
	v_fma_f32 v44, v44, s47, v16
	v_fma_f32 v45, v45, s47, v17
	v_fma_f32 v46, v46, s47, v18
	v_fma_f32 v47, v47, s47, v19
	ds_write_b32 v139, v44 offset:2048
	ds_write_b32 v139, v45 offset:6208
	ds_write_b32 v139, v46 offset:10368
	ds_write_b32 v139, v47 offset:14528
	v_sub_f32_e32 v44, v24, v141
	v_sub_f32_e32 v45, v25, v141
	v_sub_f32_e32 v46, v26, v141
	v_sub_f32_e32 v47, v27, v141
	v_fma_f32 v44, v44, s47, v20
	v_fma_f32 v45, v45, s47, v21
	v_fma_f32 v46, v46, s47, v22
	v_fma_f32 v47, v47, s47, v23
	ds_write_b32 v139, v44 offset:2560
	ds_write_b32 v139, v45 offset:6720
	ds_write_b32 v139, v46 offset:10880
	ds_write_b32 v139, v47 offset:15040
	s_nop 9
	s_waitcnt lgkmcnt(0)
	v_sub_f32_e32 v44, v24, v142
	v_sub_f32_e32 v45, v25, v142
	v_sub_f32_e32 v46, v26, v142
	v_sub_f32_e32 v47, v27, v142
	v_fma_f32 v44, v44, s47, v160
	v_fma_f32 v45, v45, s47, v161
	v_fma_f32 v46, v46, s47, v162
	v_fma_f32 v47, v47, s47, v163
	ds_write_b32 v139, v44 offset:3072
	ds_write_b32 v139, v45 offset:7232
	ds_write_b32 v139, v46 offset:11392
	ds_write_b32 v139, v47 offset:15552
	v_sub_f32_e32 v44, v24, v143
	v_sub_f32_e32 v45, v25, v143
	v_sub_f32_e32 v46, v26, v143
	v_sub_f32_e32 v47, v27, v143
	v_fma_f32 v44, v44, s47, v166
	v_fma_f32 v45, v45, s47, v167
	v_fma_f32 v46, v46, s47, v168
	v_fma_f32 v47, v47, s47, v169
	ds_write_b32 v139, v44 offset:3584
	ds_write_b32 v139, v45 offset:7744
	ds_write_b32 v139, v46 offset:11904
	ds_write_b32 v139, v47 offset:16064
	s_movk_i32 s3, 0x2080
	v_mad_u32_u24 v6, v50, s3, v165
	v_add_u32_e32 v7, 0, v6
	v_lshlrev_b32_e32 v8, 1, v50
	v_add_u32_e32 v0, 0x2100, v7
	v_mul_u32_u24_e32 v4, 0x2080, v50
	v_or_b32_e32 v1, 0x400, v8
	v_mov_b32_e32 v2, 0xff800000
	s_mov_b64 s[6:7], 0
	s_movk_i32 s3, 0x3cf
	v_mov_b32_e32 v5, v0
	v_mov_b32_e32 v9, v148
	v_mov_b32_e32 v3, 0xff800000
	s_waitcnt lgkmcnt(0)
	s_barrier
	s_branch .LBB0_1354
